# EpiResFinal pass-1: residual loads rotating 2-deep prefetch into dead fragment regs (was load->wait per 16-row site)
# baseline (speedup 1.0000x reference)
; #define LAS __attribute__((address_space(3)))
; __device__ __forceinline__ float bflo(unsigned w) { return __uint_as_float(w << 16); }
; __device__ __forceinline__ float bfhi(unsigned w) { return __uint_as_float(w & 0xffff0000u); }
;     __device__ __forceinline__ void operator()(const f32x4 (&acc)[2][2][4][2], const Unit& u, int wr, int wc, int fr, int fq, const LAS float* rsl) const {
;     ...
; #pragma unroll
;         for (int ai = 0; ai < 2; ++ai) {
; #pragma unroll
;             for (int m = 0; m < 4; ++m) { float s = 0.f;
;                 u32x4 g2[2];
; #pragma unroll
;                 for (int bj = 0; bj < 2; ++bj) g2[bj] = *(const u32x4*)(xb + (size_t)(row0 + ai * 128 + m * 16) * 1024 + u.pn * 256 + bj * 128 + wc * 32 + 8 * fq);
; #pragma unroll
;                 for (int bj = 0; bj < 2; ++bj) { const u32x4 gg = g2[bj]; f32x4 v0 = acc[ai][bj][m][0], v1 = acc[ai][bj][m][1];
;                     v0[0] += bflo(gg.x); v0[1] += bfhi(gg.x); v0[2] += bflo(gg.y); v0[3] += bfhi(gg.y); v1[0] += bflo(gg.z); v1[1] += bfhi(gg.z); v1[2] += bflo(gg.w); v1[3] += bfhi(gg.w);
;                     s += (v0[0] * v0[0] + v0[1] * v0[1]) + (v0[2] * v0[2] + v0[3] * v0[3]) + (v1[0] * v1[0] + v1[1] * v1[1]) + (v1[2] * v1[2] + v1[3] * v1[3]); }
;                 s += __shfl_xor(s, 16); s += __shfl_xor(s, 32);
;                 if (fq == 0) *(LAS float*)(lx + ((ai * 128 + wr * 64 + m * 16 + fr) * 4 + wc) * 4) = s;
;                 if (m & 1) asm volatile("" ::: "memory"); }
.LBB0_137:
	v_and_b32_e32 v131, 64, v223
	v_xor_b32_e32 v130, 16, v223
	v_add_u32_e32 v131, 64, v131
	v_lshl_add_u32 v184, s57, 8, v206
	s_lshl_b32 s0, s6, 8
	v_cmp_lt_i32_e32 vcc, v130, v131
	v_xor_b32_e32 v132, 32, v223
	s_ashr_i32 s1, s0, 31
	v_cndmask_b32_e32 v130, v223, v130, vcc
	v_cmp_lt_i32_e32 vcc, v132, v131
	v_ashrrev_i32_e32 v185, 31, v184
	v_lshl_add_u64 v[128:129], s[0:1], 1, v[164:165]
	v_cndmask_b32_e32 v131, v223, v132, vcc
	v_lshlrev_b64 v[132:133], 11, v[184:185]
	v_lshl_add_u64 v[194:195], v[128:129], 0, v[132:133]
	s_load_dwordx4 s[16:19], s[62:63], 0x78
	global_load_dwordx4 v[228:231], v[194:195], off
	global_load_dwordx4 v[232:235], v[194:195], off offset:256
	s_mov_b32 s2, 0x8000
	s_mov_b32 s3, 0
	v_lshl_add_u64 v[240:241], v[194:195], 0, s[2:3]
	global_load_dwordx4 v[236:239], v[240:241], off
	global_load_dwordx4 v[240:243], v[240:241], off offset:256
	v_lshlrev_b32_e32 v130, 2, v130
	v_lshlrev_b32_e32 v131, 2, v131
	s_waitcnt vmcnt(2)
	v_mov_b32_e32 v132, v228
	v_mov_b32_e32 v133, v229
	v_mov_b32_e32 v134, v230
	v_mov_b32_e32 v135, v231
	v_mov_b32_e32 v136, v232
	v_mov_b32_e32 v137, v233
	v_mov_b32_e32 v138, v234
	v_mov_b32_e32 v139, v235
	s_mov_b32 s2, 0x10000
	s_mov_b32 s3, 0
	v_lshl_add_u64 v[232:233], v[194:195], 0, s[2:3]
	global_load_dwordx4 v[228:231], v[232:233], off
	global_load_dwordx4 v[232:235], v[232:233], off offset:256
	v_lshlrev_b32_e32 v140, 16, v132
	v_and_b32_e32 v132, 0xffff0000, v132
	v_lshlrev_b32_e32 v141, 16, v133
	v_and_b32_e32 v133, 0xffff0000, v133
	v_add_f32_e32 v132, v125, v132
	v_add_f32_e32 v133, v127, v133
	v_add_f32_e32 v140, v124, v140
	v_add_f32_e32 v141, v126, v141
	v_lshlrev_b32_e32 v142, 16, v134
	v_and_b32_e32 v134, 0xffff0000, v134
	v_mul_f32_e32 v132, v132, v132
	v_mul_f32_e32 v133, v133, v133
	v_add_f32_e32 v134, v121, v134
	v_fmac_f32_e32 v132, v140, v140
	v_fmac_f32_e32 v133, v141, v141
	v_add_f32_e32 v142, v120, v142
	v_lshlrev_b32_e32 v143, 16, v135
	v_and_b32_e32 v135, 0xffff0000, v135
	v_add_f32_e32 v132, v132, v133
	v_mul_f32_e32 v133, v134, v134
	v_add_f32_e32 v135, v123, v135
	v_fmac_f32_e32 v133, v142, v142
	v_add_f32_e32 v143, v122, v143
	v_add_f32_e32 v132, v133, v132
	v_mul_f32_e32 v133, v135, v135
	v_fmac_f32_e32 v133, v143, v143
	v_and_b32_e32 v134, 0xffff0000, v136
	v_add_f32_e32 v132, v133, v132
	v_lshlrev_b32_e32 v133, 16, v136
	v_add_f32_e32 v134, v117, v134
	v_and_b32_e32 v136, 0xffff0000, v137
	v_add_f32_e32 v133, v116, v133
	v_lshlrev_b32_e32 v135, 16, v137
	v_add_f32_e32 v136, v119, v136
	v_mul_f32_e32 v134, v134, v134
	v_add_f32_e32 v135, v118, v135
	v_lshlrev_b32_e32 v137, 16, v138
	v_and_b32_e32 v138, 0xffff0000, v138
	v_fmac_f32_e32 v134, v133, v133
	v_mul_f32_e32 v133, v136, v136
	v_add_f32_e32 v138, v113, v138
	v_fmac_f32_e32 v133, v135, v135
	v_add_f32_e32 v137, v112, v137
	v_lshlrev_b32_e32 v140, 16, v139
	v_and_b32_e32 v139, 0xffff0000, v139
	v_add_f32_e32 v133, v134, v133
	v_mul_f32_e32 v134, v138, v138
	v_add_f32_e32 v139, v115, v139
	v_fmac_f32_e32 v134, v137, v137
	v_add_f32_e32 v140, v114, v140
	v_add_f32_e32 v133, v134, v133
	v_mul_f32_e32 v134, v139, v139
	v_fmac_f32_e32 v134, v140, v140
	v_add_f32_e32 v133, v134, v133
	v_add_f32_e32 v132, v132, v133
	ds_bpermute_b32 v133, v130, v132
	s_waitcnt lgkmcnt(0)
	v_add_f32_e32 v132, v132, v133
	ds_bpermute_b32 v133, v131, v132
	s_and_saveexec_b64 s[2:3], s[10:11]
	s_cbranch_execz .LBB0_139
	s_waitcnt lgkmcnt(0)
	v_add_f32_e32 v132, v132, v133
	ds_write_b32 v211, v132
.LBB0_139:
	s_or_b64 exec, exec, s[2:3]
	v_or_b32_e32 v182, 16, v184
	v_ashrrev_i32_e32 v183, 31, v182
	s_waitcnt lgkmcnt(0)
	v_lshlrev_b64 v[132:133], 11, v[182:183]
	v_lshl_add_u64 v[202:203], v[128:129], 0, v[132:133]
	s_waitcnt vmcnt(2)
	v_mov_b32_e32 v132, v236
	v_mov_b32_e32 v133, v237
	v_mov_b32_e32 v134, v238
	v_mov_b32_e32 v135, v239
	v_mov_b32_e32 v136, v240
	v_mov_b32_e32 v137, v241
	v_mov_b32_e32 v138, v242
	v_mov_b32_e32 v139, v243
	s_mov_b32 s2, 0x18000
	s_mov_b32 s3, 0
	v_lshl_add_u64 v[240:241], v[194:195], 0, s[2:3]
	global_load_dwordx4 v[236:239], v[240:241], off
	global_load_dwordx4 v[240:243], v[240:241], off offset:256
	v_lshlrev_b32_e32 v140, 16, v132
	v_and_b32_e32 v132, 0xffff0000, v132
	v_lshlrev_b32_e32 v141, 16, v133
	v_and_b32_e32 v133, 0xffff0000, v133
	v_add_f32_e32 v132, v109, v132
	v_add_f32_e32 v133, v111, v133
	v_add_f32_e32 v140, v108, v140
	v_add_f32_e32 v141, v110, v141
	v_lshlrev_b32_e32 v142, 16, v134
	v_and_b32_e32 v134, 0xffff0000, v134
	v_mul_f32_e32 v132, v132, v132
	v_mul_f32_e32 v133, v133, v133
	v_add_f32_e32 v134, v105, v134
	v_fmac_f32_e32 v132, v140, v140
	v_fmac_f32_e32 v133, v141, v141
	v_add_f32_e32 v142, v104, v142
	v_lshlrev_b32_e32 v143, 16, v135
	v_and_b32_e32 v135, 0xffff0000, v135
	v_add_f32_e32 v132, v132, v133
	v_mul_f32_e32 v133, v134, v134
	v_add_f32_e32 v135, v107, v135
	v_fmac_f32_e32 v133, v142, v142
	v_add_f32_e32 v143, v106, v143
	v_add_f32_e32 v132, v133, v132
	v_mul_f32_e32 v133, v135, v135
	v_fmac_f32_e32 v133, v143, v143
	v_and_b32_e32 v134, 0xffff0000, v136
	v_add_f32_e32 v132, v133, v132
	v_lshlrev_b32_e32 v133, 16, v136
	v_add_f32_e32 v134, v101, v134
	v_and_b32_e32 v136, 0xffff0000, v137
	v_add_f32_e32 v133, v100, v133
	v_lshlrev_b32_e32 v135, 16, v137
	v_add_f32_e32 v136, v103, v136
	v_mul_f32_e32 v134, v134, v134
	v_add_f32_e32 v135, v102, v135
	v_lshlrev_b32_e32 v137, 16, v138
	v_and_b32_e32 v138, 0xffff0000, v138
	v_fmac_f32_e32 v134, v133, v133
	v_mul_f32_e32 v133, v136, v136
	v_add_f32_e32 v138, v97, v138
	v_fmac_f32_e32 v133, v135, v135
	v_add_f32_e32 v137, v96, v137
	v_lshlrev_b32_e32 v140, 16, v139
	v_and_b32_e32 v139, 0xffff0000, v139
	v_add_f32_e32 v133, v134, v133
	v_mul_f32_e32 v134, v138, v138
	v_add_f32_e32 v139, v99, v139
	v_fmac_f32_e32 v134, v137, v137
	v_add_f32_e32 v140, v98, v140
	v_add_f32_e32 v133, v134, v133
	v_mul_f32_e32 v134, v139, v139
	v_fmac_f32_e32 v134, v140, v140
	v_add_f32_e32 v133, v134, v133
	v_add_f32_e32 v132, v132, v133
	ds_bpermute_b32 v133, v130, v132
	s_waitcnt lgkmcnt(0)
	v_add_f32_e32 v132, v132, v133
	ds_bpermute_b32 v133, v131, v132
	s_and_saveexec_b64 s[2:3], s[10:11]
	s_cbranch_execz .LBB0_141
	s_waitcnt lgkmcnt(0)
	v_add_f32_e32 v132, v132, v133
	ds_write_b32 v227, v132
; #define LAS __attribute__((address_space(3)))
; __device__ __forceinline__ float bflo(unsigned w) { return __uint_as_float(w << 16); }
; __device__ __forceinline__ float bfhi(unsigned w) { return __uint_as_float(w & 0xffff0000u); }
;     __device__ __forceinline__ void operator()(const f32x4 (&acc)[2][2][4][2], const Unit& u, int wr, int wc, int fr, int fq, const LAS float* rsl) const {
;     ...
; #pragma unroll
;         for (int ai = 0; ai < 2; ++ai) {
; #pragma unroll
;             for (int m = 0; m < 4; ++m) { float s = 0.f;
;                 u32x4 g2[2];
; #pragma unroll
;                 for (int bj = 0; bj < 2; ++bj) g2[bj] = *(const u32x4*)(xb + (size_t)(row0 + ai * 128 + m * 16) * 1024 + u.pn * 256 + bj * 128 + wc * 32 + 8 * fq);
; #pragma unroll
;                 for (int bj = 0; bj < 2; ++bj) { const u32x4 gg = g2[bj]; f32x4 v0 = acc[ai][bj][m][0], v1 = acc[ai][bj][m][1];
;                     v0[0] += bflo(gg.x); v0[1] += bfhi(gg.x); v0[2] += bflo(gg.y); v0[3] += bfhi(gg.y); v1[0] += bflo(gg.z); v1[1] += bfhi(gg.z); v1[2] += bflo(gg.w); v1[3] += bfhi(gg.w);
;                     s += (v0[0] * v0[0] + v0[1] * v0[1]) + (v0[2] * v0[2] + v0[3] * v0[3]) + (v1[0] * v1[0] + v1[1] * v1[1]) + (v1[2] * v1[2] + v1[3] * v1[3]); }
;                 s += __shfl_xor(s, 16); s += __shfl_xor(s, 32);
;                 if (fq == 0) *(LAS float*)(lx + ((ai * 128 + wr * 64 + m * 16 + fr) * 4 + wc) * 4) = s;
;                 if (m & 1) asm volatile("" ::: "memory"); }
.LBB0_141:
	s_or_b64 exec, exec, s[2:3]
	v_or_b32_e32 v190, 32, v184
	v_ashrrev_i32_e32 v191, 31, v190
	s_waitcnt lgkmcnt(0)
	v_lshlrev_b64 v[132:133], 11, v[190:191]
	v_lshl_add_u64 v[192:193], v[128:129], 0, v[132:133]
	s_waitcnt vmcnt(2)
	v_mov_b32_e32 v132, v228
	v_mov_b32_e32 v133, v229
	v_mov_b32_e32 v134, v230
	v_mov_b32_e32 v135, v231
	v_mov_b32_e32 v136, v232
	v_mov_b32_e32 v137, v233
	v_mov_b32_e32 v138, v234
	v_mov_b32_e32 v139, v235
	s_mov_b32 s2, 0x40000
	s_mov_b32 s3, 0
	v_lshl_add_u64 v[232:233], v[194:195], 0, s[2:3]
	global_load_dwordx4 v[228:231], v[232:233], off
	global_load_dwordx4 v[232:235], v[232:233], off offset:256
	v_lshlrev_b32_e32 v140, 16, v132
	v_and_b32_e32 v132, 0xffff0000, v132
	v_lshlrev_b32_e32 v141, 16, v133
	v_and_b32_e32 v133, 0xffff0000, v133
	v_add_f32_e32 v132, v93, v132
	v_add_f32_e32 v133, v95, v133
	v_add_f32_e32 v140, v92, v140
	v_add_f32_e32 v141, v94, v141
	v_lshlrev_b32_e32 v142, 16, v134
	v_and_b32_e32 v134, 0xffff0000, v134
	v_mul_f32_e32 v132, v132, v132
	v_mul_f32_e32 v133, v133, v133
	v_add_f32_e32 v134, v89, v134
	v_fmac_f32_e32 v132, v140, v140
	v_fmac_f32_e32 v133, v141, v141
	v_add_f32_e32 v142, v88, v142
	v_lshlrev_b32_e32 v143, 16, v135
	v_and_b32_e32 v135, 0xffff0000, v135
	v_add_f32_e32 v132, v132, v133
	v_mul_f32_e32 v133, v134, v134
	v_add_f32_e32 v135, v91, v135
	v_fmac_f32_e32 v133, v142, v142
	v_add_f32_e32 v143, v90, v143
	v_add_f32_e32 v132, v133, v132
	v_mul_f32_e32 v133, v135, v135
	v_fmac_f32_e32 v133, v143, v143
	v_and_b32_e32 v134, 0xffff0000, v136
	v_add_f32_e32 v132, v133, v132
	v_lshlrev_b32_e32 v133, 16, v136
	v_add_f32_e32 v134, v85, v134
	v_and_b32_e32 v136, 0xffff0000, v137
	v_add_f32_e32 v133, v84, v133
	v_lshlrev_b32_e32 v135, 16, v137
	v_add_f32_e32 v136, v87, v136
	v_mul_f32_e32 v134, v134, v134
	v_add_f32_e32 v135, v86, v135
	v_lshlrev_b32_e32 v137, 16, v138
	v_and_b32_e32 v138, 0xffff0000, v138
	v_fmac_f32_e32 v134, v133, v133
	v_mul_f32_e32 v133, v136, v136
	v_add_f32_e32 v138, v81, v138
	v_fmac_f32_e32 v133, v135, v135
	v_add_f32_e32 v137, v80, v137
	v_lshlrev_b32_e32 v140, 16, v139
	v_and_b32_e32 v139, 0xffff0000, v139
	v_add_f32_e32 v133, v134, v133
	v_mul_f32_e32 v134, v138, v138
	v_add_f32_e32 v139, v83, v139
	v_fmac_f32_e32 v134, v137, v137
	v_add_f32_e32 v140, v82, v140
	v_add_f32_e32 v133, v134, v133
	v_mul_f32_e32 v134, v139, v139
	v_fmac_f32_e32 v134, v140, v140
	v_add_f32_e32 v133, v134, v133
	v_add_f32_e32 v132, v132, v133
	ds_bpermute_b32 v133, v130, v132
	s_waitcnt lgkmcnt(0)
	v_add_f32_e32 v132, v132, v133
	ds_bpermute_b32 v133, v131, v132
	s_and_saveexec_b64 s[2:3], s[10:11]
	s_cbranch_execz .LBB0_143
	s_waitcnt lgkmcnt(0)
	v_add_f32_e32 v132, v132, v133
	ds_write_b32 v145, v132
.LBB0_143:
	s_or_b64 exec, exec, s[2:3]
	v_or_b32_e32 v176, 48, v184
	v_ashrrev_i32_e32 v177, 31, v176
	s_waitcnt lgkmcnt(0)
	v_lshlrev_b64 v[132:133], 11, v[176:177]
	v_lshl_add_u64 v[200:201], v[128:129], 0, v[132:133]
	s_waitcnt vmcnt(2)
	v_mov_b32_e32 v132, v236
	v_mov_b32_e32 v133, v237
	v_mov_b32_e32 v134, v238
	v_mov_b32_e32 v135, v239
	v_mov_b32_e32 v136, v240
	v_mov_b32_e32 v137, v241
	v_mov_b32_e32 v138, v242
	v_mov_b32_e32 v139, v243
	s_mov_b32 s2, 0x48000
	s_mov_b32 s3, 0
	v_lshl_add_u64 v[240:241], v[194:195], 0, s[2:3]
	global_load_dwordx4 v[236:239], v[240:241], off
	global_load_dwordx4 v[240:243], v[240:241], off offset:256
	v_lshlrev_b32_e32 v140, 16, v132
	v_and_b32_e32 v132, 0xffff0000, v132
	v_lshlrev_b32_e32 v141, 16, v133
	v_and_b32_e32 v133, 0xffff0000, v133
	v_add_f32_e32 v132, v77, v132
	v_add_f32_e32 v133, v79, v133
	v_add_f32_e32 v140, v76, v140
	v_add_f32_e32 v141, v78, v141
	v_lshlrev_b32_e32 v142, 16, v134
	v_and_b32_e32 v134, 0xffff0000, v134
	v_mul_f32_e32 v132, v132, v132
	v_mul_f32_e32 v133, v133, v133
	v_add_f32_e32 v134, v73, v134
	v_fmac_f32_e32 v132, v140, v140
	v_fmac_f32_e32 v133, v141, v141
	v_add_f32_e32 v142, v72, v142
	v_lshlrev_b32_e32 v143, 16, v135
	v_and_b32_e32 v135, 0xffff0000, v135
	v_add_f32_e32 v132, v132, v133
	v_mul_f32_e32 v133, v134, v134
	v_add_f32_e32 v135, v75, v135
	v_fmac_f32_e32 v133, v142, v142
	v_add_f32_e32 v143, v74, v143
	v_add_f32_e32 v132, v133, v132
	v_mul_f32_e32 v133, v135, v135
	v_fmac_f32_e32 v133, v143, v143
	v_and_b32_e32 v134, 0xffff0000, v136
	v_add_f32_e32 v132, v133, v132
	v_lshlrev_b32_e32 v133, 16, v136
	v_add_f32_e32 v134, v69, v134
	v_and_b32_e32 v136, 0xffff0000, v137
	v_add_f32_e32 v133, v68, v133
	v_lshlrev_b32_e32 v135, 16, v137
	v_add_f32_e32 v136, v71, v136
	v_mul_f32_e32 v134, v134, v134
	v_add_f32_e32 v135, v70, v135
	v_lshlrev_b32_e32 v137, 16, v138
	v_and_b32_e32 v138, 0xffff0000, v138
	v_fmac_f32_e32 v134, v133, v133
	v_mul_f32_e32 v133, v136, v136
	v_add_f32_e32 v138, v65, v138
	v_fmac_f32_e32 v133, v135, v135
	v_add_f32_e32 v137, v64, v137
	v_lshlrev_b32_e32 v140, 16, v139
	v_and_b32_e32 v139, 0xffff0000, v139
	v_add_f32_e32 v133, v134, v133
	v_mul_f32_e32 v134, v138, v138
	v_add_f32_e32 v139, v67, v139
	v_fmac_f32_e32 v134, v137, v137
	v_add_f32_e32 v140, v66, v140
	v_add_f32_e32 v133, v134, v133
	v_mul_f32_e32 v134, v139, v139
	v_fmac_f32_e32 v134, v140, v140
	v_add_f32_e32 v133, v134, v133
	v_add_f32_e32 v132, v132, v133
	ds_bpermute_b32 v133, v130, v132
	s_waitcnt lgkmcnt(0)
	v_add_f32_e32 v132, v132, v133
	ds_bpermute_b32 v133, v131, v132
	s_and_saveexec_b64 s[2:3], s[10:11]
	s_cbranch_execz .LBB0_145
	s_waitcnt lgkmcnt(0)
	v_add_f32_e32 v132, v132, v133
	ds_write_b32 v214, v132
; #define LAS __attribute__((address_space(3)))
; __device__ __forceinline__ float bflo(unsigned w) { return __uint_as_float(w << 16); }
; __device__ __forceinline__ float bfhi(unsigned w) { return __uint_as_float(w & 0xffff0000u); }
;     __device__ __forceinline__ void operator()(const f32x4 (&acc)[2][2][4][2], const Unit& u, int wr, int wc, int fr, int fq, const LAS float* rsl) const {
;     ...
; #pragma unroll
;         for (int ai = 0; ai < 2; ++ai) {
; #pragma unroll
;             for (int m = 0; m < 4; ++m) { float s = 0.f;
;                 u32x4 g2[2];
; #pragma unroll
;                 for (int bj = 0; bj < 2; ++bj) g2[bj] = *(const u32x4*)(xb + (size_t)(row0 + ai * 128 + m * 16) * 1024 + u.pn * 256 + bj * 128 + wc * 32 + 8 * fq);
; #pragma unroll
;                 for (int bj = 0; bj < 2; ++bj) { const u32x4 gg = g2[bj]; f32x4 v0 = acc[ai][bj][m][0], v1 = acc[ai][bj][m][1];
;                     v0[0] += bflo(gg.x); v0[1] += bfhi(gg.x); v0[2] += bflo(gg.y); v0[3] += bfhi(gg.y); v1[0] += bflo(gg.z); v1[1] += bfhi(gg.z); v1[2] += bflo(gg.w); v1[3] += bfhi(gg.w);
;                     s += (v0[0] * v0[0] + v0[1] * v0[1]) + (v0[2] * v0[2] + v0[3] * v0[3]) + (v1[0] * v1[0] + v1[1] * v1[1]) + (v1[2] * v1[2] + v1[3] * v1[3]); }
;                 s += __shfl_xor(s, 16); s += __shfl_xor(s, 32);
;                 if (fq == 0) *(LAS float*)(lx + ((ai * 128 + wr * 64 + m * 16 + fr) * 4 + wc) * 4) = s;
;                 if (m & 1) asm volatile("" ::: "memory"); }
.LBB0_145:
	s_or_b64 exec, exec, s[2:3]
	v_add_u32_e32 v186, 0x80, v184
	v_ashrrev_i32_e32 v187, 31, v186
	s_waitcnt lgkmcnt(0)
	v_lshlrev_b64 v[132:133], 11, v[186:187]
	v_lshl_add_u64 v[188:189], v[128:129], 0, v[132:133]
	s_waitcnt vmcnt(2)
	v_mov_b32_e32 v132, v228
	v_mov_b32_e32 v133, v229
	v_mov_b32_e32 v134, v230
	v_mov_b32_e32 v135, v231
	v_mov_b32_e32 v136, v232
	v_mov_b32_e32 v137, v233
	v_mov_b32_e32 v138, v234
	v_mov_b32_e32 v139, v235
	s_mov_b32 s2, 0x50000
	s_mov_b32 s3, 0
	v_lshl_add_u64 v[232:233], v[194:195], 0, s[2:3]
	global_load_dwordx4 v[228:231], v[232:233], off
	global_load_dwordx4 v[232:235], v[232:233], off offset:256
	v_lshlrev_b32_e32 v140, 16, v132
	v_and_b32_e32 v132, 0xffff0000, v132
	v_lshlrev_b32_e32 v141, 16, v133
	v_and_b32_e32 v133, 0xffff0000, v133
	v_add_f32_e32 v132, v61, v132
	v_add_f32_e32 v133, v63, v133
	v_add_f32_e32 v140, v60, v140
	v_add_f32_e32 v141, v62, v141
	v_lshlrev_b32_e32 v142, 16, v134
	v_and_b32_e32 v134, 0xffff0000, v134
	v_mul_f32_e32 v132, v132, v132
	v_mul_f32_e32 v133, v133, v133
	v_add_f32_e32 v134, v57, v134
	v_fmac_f32_e32 v132, v140, v140
	v_fmac_f32_e32 v133, v141, v141
	v_add_f32_e32 v142, v56, v142
	v_lshlrev_b32_e32 v143, 16, v135
	v_and_b32_e32 v135, 0xffff0000, v135
	v_add_f32_e32 v132, v132, v133
	v_mul_f32_e32 v133, v134, v134
	v_add_f32_e32 v135, v59, v135
	v_fmac_f32_e32 v133, v142, v142
	v_add_f32_e32 v143, v58, v143
	v_add_f32_e32 v132, v133, v132
	v_mul_f32_e32 v133, v135, v135
	v_fmac_f32_e32 v133, v143, v143
	v_and_b32_e32 v134, 0xffff0000, v136
	v_add_f32_e32 v132, v133, v132
	v_lshlrev_b32_e32 v133, 16, v136
	v_add_f32_e32 v134, v53, v134
	v_and_b32_e32 v136, 0xffff0000, v137
	v_add_f32_e32 v133, v52, v133
	v_lshlrev_b32_e32 v135, 16, v137
	v_add_f32_e32 v136, v55, v136
	v_mul_f32_e32 v134, v134, v134
	v_add_f32_e32 v135, v54, v135
	v_lshlrev_b32_e32 v137, 16, v138
	v_and_b32_e32 v138, 0xffff0000, v138
	v_fmac_f32_e32 v134, v133, v133
	v_mul_f32_e32 v133, v136, v136
	v_add_f32_e32 v138, v49, v138
	v_fmac_f32_e32 v133, v135, v135
	v_add_f32_e32 v137, v48, v137
	v_lshlrev_b32_e32 v140, 16, v139
	v_and_b32_e32 v139, 0xffff0000, v139
	v_add_f32_e32 v133, v134, v133
	v_mul_f32_e32 v134, v138, v138
	v_add_f32_e32 v139, v51, v139
	v_fmac_f32_e32 v134, v137, v137
	v_add_f32_e32 v140, v50, v140
	v_add_f32_e32 v133, v134, v133
	v_mul_f32_e32 v134, v139, v139
	v_fmac_f32_e32 v134, v140, v140
	v_add_f32_e32 v133, v134, v133
	v_add_f32_e32 v132, v132, v133
	ds_bpermute_b32 v133, v130, v132
	s_waitcnt lgkmcnt(0)
	v_add_f32_e32 v132, v132, v133
	ds_bpermute_b32 v133, v131, v132
	s_and_saveexec_b64 s[2:3], s[10:11]
	s_cbranch_execz .LBB0_147
	s_waitcnt lgkmcnt(0)
	v_add_f32_e32 v132, v132, v133
	ds_write_b32 v215, v132
.LBB0_147:
	s_or_b64 exec, exec, s[2:3]
	v_add_u32_e32 v174, 0x90, v184
	v_ashrrev_i32_e32 v175, 31, v174
	s_waitcnt lgkmcnt(0)
	v_lshlrev_b64 v[132:133], 11, v[174:175]
	v_lshl_add_u64 v[198:199], v[128:129], 0, v[132:133]
	s_waitcnt vmcnt(2)
	v_mov_b32_e32 v132, v236
	v_mov_b32_e32 v133, v237
	v_mov_b32_e32 v134, v238
	v_mov_b32_e32 v135, v239
	v_mov_b32_e32 v136, v240
	v_mov_b32_e32 v137, v241
	v_mov_b32_e32 v138, v242
	v_mov_b32_e32 v139, v243
	s_mov_b32 s2, 0x58000
	s_mov_b32 s3, 0
	v_lshl_add_u64 v[240:241], v[194:195], 0, s[2:3]
	global_load_dwordx4 v[236:239], v[240:241], off
	global_load_dwordx4 v[240:243], v[240:241], off offset:256
	v_lshlrev_b32_e32 v140, 16, v132
	v_and_b32_e32 v132, 0xffff0000, v132
	v_lshlrev_b32_e32 v141, 16, v133
	v_and_b32_e32 v133, 0xffff0000, v133
	v_add_f32_e32 v132, v45, v132
	v_add_f32_e32 v133, v47, v133
	v_add_f32_e32 v140, v44, v140
	v_add_f32_e32 v141, v46, v141
	v_lshlrev_b32_e32 v142, 16, v134
	v_and_b32_e32 v134, 0xffff0000, v134
	v_mul_f32_e32 v132, v132, v132
	v_mul_f32_e32 v133, v133, v133
	v_add_f32_e32 v134, v41, v134
	v_fmac_f32_e32 v132, v140, v140
	v_fmac_f32_e32 v133, v141, v141
	v_add_f32_e32 v142, v40, v142
	v_lshlrev_b32_e32 v143, 16, v135
	v_and_b32_e32 v135, 0xffff0000, v135
	v_add_f32_e32 v132, v132, v133
	v_mul_f32_e32 v133, v134, v134
	v_add_f32_e32 v135, v43, v135
	v_fmac_f32_e32 v133, v142, v142
	v_add_f32_e32 v143, v42, v143
	v_add_f32_e32 v132, v133, v132
	v_mul_f32_e32 v133, v135, v135
	v_fmac_f32_e32 v133, v143, v143
	v_and_b32_e32 v134, 0xffff0000, v136
	v_add_f32_e32 v132, v133, v132
	v_lshlrev_b32_e32 v133, 16, v136
	v_add_f32_e32 v134, v37, v134
	v_and_b32_e32 v136, 0xffff0000, v137
	v_add_f32_e32 v133, v36, v133
	v_lshlrev_b32_e32 v135, 16, v137
	v_add_f32_e32 v136, v39, v136
	v_mul_f32_e32 v134, v134, v134
	v_add_f32_e32 v135, v38, v135
	v_lshlrev_b32_e32 v137, 16, v138
	v_and_b32_e32 v138, 0xffff0000, v138
	v_fmac_f32_e32 v134, v133, v133
	v_mul_f32_e32 v133, v136, v136
	v_add_f32_e32 v138, v33, v138
	v_fmac_f32_e32 v133, v135, v135
	v_add_f32_e32 v137, v32, v137
	v_lshlrev_b32_e32 v140, 16, v139
	v_and_b32_e32 v139, 0xffff0000, v139
	v_add_f32_e32 v133, v134, v133
	v_mul_f32_e32 v134, v138, v138
	v_add_f32_e32 v139, v35, v139
	v_fmac_f32_e32 v134, v137, v137
	v_add_f32_e32 v140, v34, v140
	v_add_f32_e32 v133, v134, v133
	v_mul_f32_e32 v134, v139, v139
	v_fmac_f32_e32 v134, v140, v140
	v_add_f32_e32 v133, v134, v133
	v_add_f32_e32 v132, v132, v133
	ds_bpermute_b32 v133, v130, v132
	s_waitcnt lgkmcnt(0)
	v_add_f32_e32 v132, v132, v133
	ds_bpermute_b32 v133, v131, v132
	s_and_saveexec_b64 s[2:3], s[10:11]
	s_cbranch_execz .LBB0_149
	s_waitcnt lgkmcnt(0)
	v_add_f32_e32 v132, v132, v133
	ds_write_b32 v216, v132
; #define LAS __attribute__((address_space(3)))
; __device__ __forceinline__ float bflo(unsigned w) { return __uint_as_float(w << 16); }
; __device__ __forceinline__ float bfhi(unsigned w) { return __uint_as_float(w & 0xffff0000u); }
;     __device__ __forceinline__ void operator()(const f32x4 (&acc)[2][2][4][2], const Unit& u, int wr, int wc, int fr, int fq, const LAS float* rsl) const {
;     ...
; #pragma unroll
;         for (int ai = 0; ai < 2; ++ai) {
; #pragma unroll
;             for (int m = 0; m < 4; ++m) { float s = 0.f;
;                 u32x4 g2[2];
; #pragma unroll
;                 for (int bj = 0; bj < 2; ++bj) g2[bj] = *(const u32x4*)(xb + (size_t)(row0 + ai * 128 + m * 16) * 1024 + u.pn * 256 + bj * 128 + wc * 32 + 8 * fq);
; #pragma unroll
;                 for (int bj = 0; bj < 2; ++bj) { const u32x4 gg = g2[bj]; f32x4 v0 = acc[ai][bj][m][0], v1 = acc[ai][bj][m][1];
;                     v0[0] += bflo(gg.x); v0[1] += bfhi(gg.x); v0[2] += bflo(gg.y); v0[3] += bfhi(gg.y); v1[0] += bflo(gg.z); v1[1] += bfhi(gg.z); v1[2] += bflo(gg.w); v1[3] += bfhi(gg.w);
;                     s += (v0[0] * v0[0] + v0[1] * v0[1]) + (v0[2] * v0[2] + v0[3] * v0[3]) + (v1[0] * v1[0] + v1[1] * v1[1]) + (v1[2] * v1[2] + v1[3] * v1[3]); }
;                 s += __shfl_xor(s, 16); s += __shfl_xor(s, 32);
;                 if (fq == 0) *(LAS float*)(lx + ((ai * 128 + wr * 64 + m * 16 + fr) * 4 + wc) * 4) = s;
;                 if (m & 1) asm volatile("" ::: "memory"); }
.LBB0_149:
	s_or_b64 exec, exec, s[2:3]
	v_add_u32_e32 v178, 0xa0, v184
	v_ashrrev_i32_e32 v179, 31, v178
	s_waitcnt lgkmcnt(0)
	v_lshlrev_b64 v[132:133], 11, v[178:179]
	v_lshl_add_u64 v[180:181], v[128:129], 0, v[132:133]
	s_waitcnt vmcnt(2)
	v_mov_b32_e32 v132, v228
	v_mov_b32_e32 v133, v229
	v_mov_b32_e32 v134, v230
	v_mov_b32_e32 v135, v231
	v_mov_b32_e32 v136, v232
	v_mov_b32_e32 v137, v233
	v_mov_b32_e32 v138, v234
	v_mov_b32_e32 v139, v235
	v_lshlrev_b32_e32 v140, 16, v132
	v_and_b32_e32 v132, 0xffff0000, v132
	v_lshlrev_b32_e32 v141, 16, v133
	v_and_b32_e32 v133, 0xffff0000, v133
	v_add_f32_e32 v132, v29, v132
	v_add_f32_e32 v133, v31, v133
	v_add_f32_e32 v140, v28, v140
	v_add_f32_e32 v141, v30, v141
	v_lshlrev_b32_e32 v142, 16, v134
	v_and_b32_e32 v134, 0xffff0000, v134
	v_mul_f32_e32 v132, v132, v132
	v_mul_f32_e32 v133, v133, v133
	v_add_f32_e32 v134, v25, v134
	v_fmac_f32_e32 v132, v140, v140
	v_fmac_f32_e32 v133, v141, v141
	v_add_f32_e32 v142, v24, v142
	v_lshlrev_b32_e32 v143, 16, v135
	v_and_b32_e32 v135, 0xffff0000, v135
	v_add_f32_e32 v132, v132, v133
	v_mul_f32_e32 v133, v134, v134
	v_add_f32_e32 v135, v27, v135
	v_fmac_f32_e32 v133, v142, v142
	v_add_f32_e32 v143, v26, v143
	v_add_f32_e32 v132, v133, v132
	v_mul_f32_e32 v133, v135, v135
	v_fmac_f32_e32 v133, v143, v143
	v_and_b32_e32 v134, 0xffff0000, v136
	v_add_f32_e32 v132, v133, v132
	v_lshlrev_b32_e32 v133, 16, v136
	v_add_f32_e32 v134, v21, v134
	v_and_b32_e32 v136, 0xffff0000, v137
	v_add_f32_e32 v133, v20, v133
	v_lshlrev_b32_e32 v135, 16, v137
	v_add_f32_e32 v136, v23, v136
	v_mul_f32_e32 v134, v134, v134
	v_add_f32_e32 v135, v22, v135
	v_lshlrev_b32_e32 v137, 16, v138
	v_and_b32_e32 v138, 0xffff0000, v138
	v_fmac_f32_e32 v134, v133, v133
	v_mul_f32_e32 v133, v136, v136
	v_add_f32_e32 v138, v17, v138
	v_fmac_f32_e32 v133, v135, v135
	v_add_f32_e32 v137, v16, v137
	v_lshlrev_b32_e32 v140, 16, v139
	v_and_b32_e32 v139, 0xffff0000, v139
	v_add_f32_e32 v133, v134, v133
	v_mul_f32_e32 v134, v138, v138
	v_add_f32_e32 v139, v19, v139
	v_fmac_f32_e32 v134, v137, v137
	v_add_f32_e32 v140, v18, v140
	v_add_f32_e32 v133, v134, v133
	v_mul_f32_e32 v134, v139, v139
	v_fmac_f32_e32 v134, v140, v140
	v_add_f32_e32 v133, v134, v133
	v_add_f32_e32 v132, v132, v133
	ds_bpermute_b32 v133, v130, v132
	s_waitcnt lgkmcnt(0)
	v_add_f32_e32 v132, v132, v133
	ds_bpermute_b32 v133, v131, v132
	s_and_saveexec_b64 s[2:3], s[10:11]
	s_cbranch_execz .LBB0_151
	s_waitcnt lgkmcnt(0)
	v_add_f32_e32 v132, v132, v133
	ds_write_b32 v217, v132
.LBB0_151:
	s_or_b64 exec, exec, s[2:3]
	v_add_u32_e32 v172, 0xb0, v184
	v_ashrrev_i32_e32 v173, 31, v172
	s_waitcnt lgkmcnt(0)
	v_lshlrev_b64 v[132:133], 11, v[172:173]
	v_lshl_add_u64 v[196:197], v[128:129], 0, v[132:133]
	s_waitcnt vmcnt(0)
	v_mov_b32_e32 v132, v236
	v_mov_b32_e32 v133, v237
	v_mov_b32_e32 v134, v238
	v_mov_b32_e32 v135, v239
	v_mov_b32_e32 v136, v240
	v_mov_b32_e32 v137, v241
	v_mov_b32_e32 v138, v242
	v_mov_b32_e32 v139, v243
	v_and_b32_e32 v129, 0xffff0000, v132
	v_lshlrev_b32_e32 v128, 16, v132
	v_add_f32_e32 v129, v13, v129
	v_lshlrev_b32_e32 v132, 16, v133
	v_and_b32_e32 v133, 0xffff0000, v133
	v_add_f32_e32 v128, v12, v128
	v_add_f32_e32 v133, v15, v133
	v_mul_f32_e32 v129, v129, v129
	v_add_f32_e32 v132, v14, v132
	v_lshlrev_b32_e32 v140, 16, v134
	v_and_b32_e32 v134, 0xffff0000, v134
	v_fmac_f32_e32 v129, v128, v128
	v_mul_f32_e32 v128, v133, v133
	v_add_f32_e32 v134, v9, v134
	v_fmac_f32_e32 v128, v132, v132
	v_add_f32_e32 v140, v8, v140
	v_lshlrev_b32_e32 v141, 16, v135
	v_and_b32_e32 v135, 0xffff0000, v135
	v_add_f32_e32 v128, v129, v128
	v_mul_f32_e32 v129, v134, v134
	v_add_f32_e32 v135, v11, v135
	v_fmac_f32_e32 v129, v140, v140
	v_add_f32_e32 v141, v10, v141
	v_add_f32_e32 v128, v129, v128
	v_mul_f32_e32 v129, v135, v135
	v_fmac_f32_e32 v129, v141, v141
	v_and_b32_e32 v132, 0xffff0000, v136
	v_add_f32_e32 v128, v129, v128
	v_lshlrev_b32_e32 v129, 16, v136
	v_add_f32_e32 v132, v5, v132
	v_and_b32_e32 v134, 0xffff0000, v137
	v_add_f32_e32 v129, v4, v129
	v_lshlrev_b32_e32 v133, 16, v137
	v_add_f32_e32 v134, v7, v134
	v_mul_f32_e32 v132, v132, v132
	v_add_f32_e32 v133, v6, v133
	v_and_b32_e32 v136, 0xffff0000, v138
	v_fmac_f32_e32 v132, v129, v129
	v_mul_f32_e32 v129, v134, v134
	v_lshlrev_b32_e32 v135, 16, v138
	v_add_f32_e32 v136, v1, v136
	v_fmac_f32_e32 v129, v133, v133
	v_add_f32_e32 v135, v0, v135
	v_and_b32_e32 v138, 0xffff0000, v139
	v_add_f32_e32 v129, v132, v129
	v_mul_f32_e32 v132, v136, v136
	v_lshlrev_b32_e32 v137, 16, v139
	v_add_f32_e32 v138, v3, v138
	v_fmac_f32_e32 v132, v135, v135
	v_add_f32_e32 v137, v2, v137
	v_add_f32_e32 v129, v132, v129
	v_mul_f32_e32 v132, v138, v138
	v_fmac_f32_e32 v132, v137, v137
	v_add_f32_e32 v129, v132, v129
	v_add_f32_e32 v128, v128, v129
	ds_bpermute_b32 v129, v130, v128
	s_waitcnt lgkmcnt(0)
	v_add_f32_e32 v128, v128, v129
	ds_bpermute_b32 v129, v131, v128
	s_and_saveexec_b64 s[2:3], s[10:11]
	s_cbranch_execz .LBB0_153
	s_waitcnt lgkmcnt(0)
	v_add_f32_e32 v128, v128, v129
	ds_write_b32 v218, v128
